# top-k rounds: compare/select pairs software-pipelined over two mask registers (31 hazard nops per round removed)
# baseline (speedup 1.0000x reference)
; __device__ __forceinline__ void nsa_unit(const Params& p, int bg, int jq, LAS unsigned char* lds, int wave, int lane, bool build_lut) {
;     ...
;         for (int round = 0; round < 13; ++round) {
;             int lm = val[0];
; #pragma unroll
;             for (int e = 1; e < 32; ++e) lm = max(lm, val[e]);
;             int gm = max(lm, __builtin_amdgcn_mov_dpp(lm, 0xB1, 0xf, 0xf, true));
;             gm = max(gm, __builtin_amdgcn_mov_dpp(gm, 0x4E, 0xf, 0xf, true));
;             gm = max(gm, __builtin_amdgcn_mov_dpp(gm, 0x141, 0xf, 0xf, true));
;             const int n = 255 - (gm & 0xff);
;             myw |= (gm >= 0 && (n >> 5) == tj) ? (1u << (n & 31)) : 0u;
; #pragma unroll
;             for (int e = 0; e < 32; ++e) val[e] = (val[e] == gm) ? -1 : val[e];
;         }
;         selw[lane] |= myw;
.LBB0_1149:
	v_max_i32_e32 v35, v2, v3
	v_max3_i32 v35, v35, v4, v5
	v_max3_i32 v35, v35, v6, v7
	v_max3_i32 v35, v35, v8, v9
	v_max3_i32 v35, v35, v10, v11
	v_max3_i32 v35, v35, v12, v13
	v_max3_i32 v35, v35, v14, v15
	v_max3_i32 v35, v35, v16, v17
	v_max3_i32 v35, v35, v18, v19
	v_max3_i32 v35, v35, v20, v21
	v_max3_i32 v35, v35, v22, v23
	v_max3_i32 v35, v35, v24, v25
	v_max3_i32 v35, v35, v26, v27
	v_max3_i32 v35, v35, v28, v29
	v_max3_i32 v35, v35, v30, v31
	v_max3_i32 v35, v35, v32, v34
	s_add_i32 s6, s6, -1
	s_nop 0
	v_max_i32_dpp v35, v35, v35 quad_perm:[1,0,3,2] row_mask:0xf bank_mask:0xf bound_ctrl:1
	s_nop 1
	v_max_i32_dpp v35, v35, v35 quad_perm:[2,3,0,1] row_mask:0xf bank_mask:0xf bound_ctrl:1
	s_nop 1
	v_max_i32_dpp v35, v35, v35 row_half_mirror row_mask:0xf bank_mask:0xf bound_ctrl:1
	v_not_b32_e32 v36, v35
	v_cmp_lt_i32_e32 vcc, -1, v35
	v_cmp_ne_u32_e64 s[4:5], v2, v35
	v_cmp_ne_u32_e64 s[100:101], v3, v35
	s_nop 0
	v_cndmask_b32_e64 v2, -1, v2, s[4:5]
	v_cmp_ne_u32_e64 s[4:5], v4, v35
	v_cndmask_b32_e64 v3, -1, v3, s[100:101]
	v_cmp_ne_u32_e64 s[100:101], v5, v35
	v_cndmask_b32_e64 v4, -1, v4, s[4:5]
	v_cmp_ne_u32_e64 s[4:5], v6, v35
	v_cndmask_b32_e64 v5, -1, v5, s[100:101]
	v_cmp_ne_u32_e64 s[100:101], v7, v35
	v_cndmask_b32_e64 v6, -1, v6, s[4:5]
	v_cmp_ne_u32_e64 s[4:5], v8, v35
	v_cndmask_b32_e64 v7, -1, v7, s[100:101]
	v_cmp_ne_u32_e64 s[100:101], v9, v35
	v_cndmask_b32_e64 v8, -1, v8, s[4:5]
	v_cmp_ne_u32_e64 s[4:5], v10, v35
	v_cndmask_b32_e64 v9, -1, v9, s[100:101]
	v_cmp_ne_u32_e64 s[100:101], v11, v35
	v_cndmask_b32_e64 v10, -1, v10, s[4:5]
	v_cmp_ne_u32_e64 s[4:5], v12, v35
	v_cndmask_b32_e64 v11, -1, v11, s[100:101]
	v_cmp_ne_u32_e64 s[100:101], v13, v35
	v_cndmask_b32_e64 v12, -1, v12, s[4:5]
	v_cmp_ne_u32_e64 s[4:5], v14, v35
	v_cndmask_b32_e64 v13, -1, v13, s[100:101]
	v_cmp_ne_u32_e64 s[100:101], v15, v35
	v_cndmask_b32_e64 v14, -1, v14, s[4:5]
	v_cmp_ne_u32_e64 s[4:5], v16, v35
	v_cndmask_b32_e64 v15, -1, v15, s[100:101]
	v_cmp_ne_u32_e64 s[100:101], v17, v35
	v_cndmask_b32_e64 v16, -1, v16, s[4:5]
	v_cmp_ne_u32_e64 s[4:5], v18, v35
	v_cndmask_b32_e64 v17, -1, v17, s[100:101]
	v_cmp_ne_u32_e64 s[100:101], v19, v35
	v_cndmask_b32_e64 v18, -1, v18, s[4:5]
	v_cmp_ne_u32_e64 s[4:5], v20, v35
	v_cndmask_b32_e64 v19, -1, v19, s[100:101]
	v_cmp_ne_u32_e64 s[100:101], v21, v35
	v_cndmask_b32_e64 v20, -1, v20, s[4:5]
	v_cmp_ne_u32_e64 s[4:5], v22, v35
	v_cndmask_b32_e64 v21, -1, v21, s[100:101]
	v_cmp_ne_u32_e64 s[100:101], v23, v35
	v_cndmask_b32_e64 v22, -1, v22, s[4:5]
	v_cmp_ne_u32_e64 s[4:5], v24, v35
	v_cndmask_b32_e64 v23, -1, v23, s[100:101]
	v_cmp_ne_u32_e64 s[100:101], v25, v35
	v_cndmask_b32_e64 v24, -1, v24, s[4:5]
	v_cmp_ne_u32_e64 s[4:5], v26, v35
	v_cndmask_b32_e64 v25, -1, v25, s[100:101]
	v_cmp_ne_u32_e64 s[100:101], v27, v35
	v_cndmask_b32_e64 v26, -1, v26, s[4:5]
	v_cmp_ne_u32_e64 s[4:5], v28, v35
	v_cndmask_b32_e64 v27, -1, v27, s[100:101]
	v_cmp_ne_u32_e64 s[100:101], v29, v35
	v_cndmask_b32_e64 v28, -1, v28, s[4:5]
	v_cmp_ne_u32_e64 s[4:5], v30, v35
	v_cndmask_b32_e64 v29, -1, v29, s[100:101]
	v_cmp_ne_u32_e64 s[100:101], v31, v35
	v_cndmask_b32_e64 v30, -1, v30, s[4:5]
	v_cmp_ne_u32_e64 s[4:5], v32, v35
	v_cndmask_b32_e64 v31, -1, v31, s[100:101]
	v_cmp_ne_u32_e64 s[100:101], v34, v35
	v_cndmask_b32_e64 v32, -1, v32, s[4:5]
	v_lshrrev_b32_e32 v35, 5, v36
	s_nop 0
	v_cndmask_b32_e64 v34, -1, v34, s[100:101]
	v_and_b32_e32 v35, 7, v35
	v_cmp_eq_u32_e64 s[4:5], v35, v118
	v_lshlrev_b32_e64 v36, v36, 1
	s_and_b64 vcc, vcc, s[4:5]
	v_cndmask_b32_e32 v35, 0, v36, vcc
	s_cmp_eq_u32 s6, 0
	v_or_b32_e32 v33, v35, v33
	s_cbranch_scc0 .LBB0_1149
	ds_read_b32 v2, v159 offset:8192
	s_waitcnt lgkmcnt(0)
	v_or_b32_e32 v2, v2, v33
	ds_write_b32 v159, v2 offset:8192

; __global__ void __launch_bounds__(NTHREADS, 2) fwd_megakernel(Params p) {
	.amdhsa_kernel _Z14fwd_megakernel6Params
		.amdhsa_group_segment_fixed_size 0
		.amdhsa_private_segment_fixed_size 0
		.amdhsa_kernarg_size 432
		.amdhsa_user_sgpr_count 2
		.amdhsa_user_sgpr_dispatch_ptr 0
		.amdhsa_user_sgpr_queue_ptr 0
		.amdhsa_user_sgpr_kernarg_segment_ptr 1
		.amdhsa_user_sgpr_dispatch_id 0
		.amdhsa_user_sgpr_kernarg_preload_length 0
		.amdhsa_user_sgpr_kernarg_preload_offset 0
		.amdhsa_user_sgpr_private_segment_size 0
		.amdhsa_uses_dynamic_stack 0
		.amdhsa_enable_private_segment 0
		.amdhsa_system_sgpr_workgroup_id_x 1
		.amdhsa_system_sgpr_workgroup_id_y 0
		.amdhsa_system_sgpr_workgroup_id_z 0
		.amdhsa_system_sgpr_workgroup_info 0
		.amdhsa_system_vgpr_workitem_id 2
		.amdhsa_next_free_vgpr 254
		.amdhsa_next_free_sgpr 102
		.amdhsa_accum_offset 256
		.amdhsa_reserve_vcc 1
		.amdhsa_float_round_mode_32 0
		.amdhsa_float_round_mode_16_64 0
		.amdhsa_float_denorm_mode_32 3
		.amdhsa_float_denorm_mode_16_64 3
		.amdhsa_dx10_clamp 1
		.amdhsa_ieee_mode 1
		.amdhsa_fp16_overflow 0
		.amdhsa_tg_split 0
		.amdhsa_exception_fp_ieee_invalid_op 0
		.amdhsa_exception_fp_denorm_src 0
		.amdhsa_exception_fp_ieee_div_zero 0
		.amdhsa_exception_fp_ieee_overflow 0
		.amdhsa_exception_fp_ieee_underflow 0
		.amdhsa_exception_fp_ieee_inexact 0
		.amdhsa_exception_int_div_zero 0
	.end_amdhsa_kernel

; __global__ void __launch_bounds__(NTHREADS, 2) fwd_megakernel(Params p) {
amdhsa.kernels:
  - .agpr_count:     0
    .args:
      - .offset:         0
        .size:           176
        .value_kind:     by_value
      - .offset:         176
        .size:           4
        .value_kind:     hidden_block_count_x
      - .offset:         180
        .size:           4
        .value_kind:     hidden_block_count_y
      - .offset:         184
        .size:           4
        .value_kind:     hidden_block_count_z
      - .offset:         188
        .size:           2
        .value_kind:     hidden_group_size_x
      - .offset:         190
        .size:           2
        .value_kind:     hidden_group_size_y
      - .offset:         192
        .size:           2
        .value_kind:     hidden_group_size_z
      - .offset:         194
        .size:           2
        .value_kind:     hidden_remainder_x
      - .offset:         196
        .size:           2
        .value_kind:     hidden_remainder_y
      - .offset:         198
        .size:           2
        .value_kind:     hidden_remainder_z
      - .offset:         216
        .size:           8
        .value_kind:     hidden_global_offset_x
      - .offset:         224
        .size:           8
        .value_kind:     hidden_global_offset_y
      - .offset:         232
        .size:           8
        .value_kind:     hidden_global_offset_z
      - .offset:         240
        .size:           2
        .value_kind:     hidden_grid_dims
      - .offset:         264
        .size:           8
        .value_kind:     hidden_multigrid_sync_arg
      - .offset:         296
        .size:           4
        .value_kind:     hidden_dynamic_lds_size
    .group_segment_fixed_size: 0
    .kernarg_segment_align: 8
    .kernarg_segment_size: 432
    .language:       OpenCL C
    .language_version:
      - 2
      - 0
    .max_flat_workgroup_size: 512
    .name:           _Z14fwd_megakernel6Params
    .private_segment_fixed_size: 0
    .sgpr_count:     108
    .sgpr_spill_count: 73
    .symbol:         _Z14fwd_megakernel6Params.kd
    .uniform_work_group_size: 1
    .uses_dynamic_stack: false
    .vgpr_count:     254
    .vgpr_spill_count: 0
    .wavefront_size: 64
